# v3 plus GEMM1 epilogue: second-row sumsq load issued together with the first (one exposed load instead of two per half)
# baseline (speedup 1.0000x reference)
; DI int crow(int i, int h) { return (i & 3) + 8 * (i >> 2) + 4 * h; }
; DI float xsum32(float v) { return v + __shfl_xor(v, 32, 64); }
; DI void epi_gemm1(const Params& p, int l, const f32x16& a0, const f32x16& a1, int token, int trow, int cb, int h, char* wl) {
;   constexpr int RS = 144;
;   const int sp = token & 8191;
;   const float rs = __builtin_amdgcn_rsqf(p.sumsq_x[l * T + token] * (1.f / 1024.f) + EPS);
;   float v[2][16];
; #pragma unroll
;   for (int i = 0; i < 16; ++i) { v[0][i] = a0[i] * rs; v[1][i] = a1[i] * rs; }
;   if (cb < 512 || (cb >= 1792 && cb < 2304)) {
;     float ss = 0.f;
; #pragma unroll
;     for (int i = 0; i < 16; ++i) ss += v[0][i] * v[0][i] + v[1][i] * v[1][i];
;     ss = xsum32(ss);
;     const float r = __builtin_amdgcn_rsqf(ss * (1.f / 64.f) + EPS);
;     const float* g; float qs = 1.f; bool rope = false;
;     if (cb < 256)       { g = p.aq_g + l * 64; qs = QSCALE64; }
;     else if (cb < 512)  { g = p.ak_g + l * 64; }
;     else if (cb < 2176) { g = p.cq_g + l * 64; qs = QSCALE64; rope = true; }
;     else                { g = p.ck_g + l * 64; rope = true; }
;     const float rq = r * qs;
; #pragma unroll
;     for (int nb = 0; nb < 2; ++nb)
; #pragma unroll
;       for (int g4 = 0; g4 < 4; ++g4) {
;         const float4 gg = *(const float4*)(g + nb * 32 + 8 * g4 + 4 * h);
;         v[nb][4 * g4] *= rq * gg.x; v[nb][4 * g4 + 1] *= rq * gg.y; v[nb][4 * g4 + 2] *= rq * gg.z; v[nb][4 * g4 + 3] *= rq * gg.w;
;       }
;     if (rope) {
; #pragma unroll
;       for (int nb = 0; nb < 2; ++nb) {
;         const int pos = nb == 0 ? (sp >> 6) : (sp & 63);
; #pragma unroll
;         for (int i = 0; i < 8; ++i) {
;           const float2 cs = p.rope[pos * 16 + crow(i, h)];
;           const float x1 = v[nb][i], x2 = v[nb][i + 8];
;           v[nb][i] = x1 * cs.x - x2 * cs.y; v[nb][i + 8] = x2 * cs.x + x1 * cs.y;
;         }
;       }
;     }
;   } else if ((cb >= 512 && cb < 768) || (cb >= 2304 && cb < 2432)) {
;   } else if (cb >= 1024 && cb < 1408) {
.LBB0_140:
	v_or_b32_e32 v134, s2, v166
	v_add_u32_e32 v136, s16, v134
	v_ashrrev_i32_e32 v137, 31, v136
	v_lshl_add_u64 v[136:137], v[136:137], 2, s[76:77]
	global_load_dword v135, v[136:137], off
	global_load_dword v216, v[136:137], off offset:128
	v_readlane_b32 s0, v255, 50
	s_or_b32 s24, s97, s0
	s_cmpk_lg_i32 s24, 0x900
	s_cselect_b64 s[0:1], -1, 0
	s_cmpk_lt_u32 s97, 0x200
	s_cselect_b64 s[8:9], -1, 0
	s_cmpk_gt_u32 s97, 0x1ff
	s_cselect_b64 s[34:35], -1, 0
	s_add_i32 s87, s24, 0xfffff900
	s_cmpk_gt_u32 s87, 0x1ff
	s_cselect_b64 s[6:7], -1, 0
	s_and_b64 s[72:73], s[34:35], s[6:7]
	s_cmpk_gt_u32 s97, 0x2ff
	s_cselect_b64 s[80:81], -1, 0
	s_and_b64 s[12:13], s[80:81], s[0:1]
	s_add_i32 s0, s24, 0xfffffc00
	s_cmpk_gt_u32 s0, 0x17f
	s_cselect_b64 s[36:37], -1, 0
	s_cmpk_gt_u32 s97, 0x4ff
	s_cselect_b64 s[0:1], -1, 0
	v_writelane_b32 v255, s0, 55
	s_cmpk_lt_u32 s97, 0x500
	s_mov_b64 s[6:7], -1
	v_writelane_b32 v255, s1, 56
	s_mov_b32 s0, 0x6160000
	s_cselect_b32 s0, s0, 0x61e0000
	v_readlane_b32 s1, v255, 43
	s_add_u32 s38, s1, s0
	v_readlane_b32 s0, v255, 44
	s_addc_u32 s39, s0, 0
	s_cmp_eq_u32 s97, 0
	s_cselect_b64 s[10:11], -1, 0
	s_cmp_lg_u32 s97, 0
	s_cselect_b64 s[18:19], -1, 0
	s_cmpk_lt_u32 s24, 0x880
	s_cselect_b64 s[14:15], -1, 0
	s_cmpk_gt_u32 s24, 0x87f
	s_cselect_b64 s[0:1], -1, 0
	v_writelane_b32 v255, s0, 57
	s_and_b64 vcc, exec, s[72:73]
	s_waitcnt vmcnt(0)
	v_fmamk_f32 v135, v135, 0x3a800000, v191
	v_rsq_f32_e32 v138, v135
	v_writelane_b32 v255, s1, 58
	v_pk_mul_f32 v[150:151], v[118:119], v[138:139] op_sel_hi:[1,0]
	v_pk_mul_f32 v[118:119], v[102:103], v[138:139] op_sel_hi:[1,0]
	v_pk_mul_f32 v[102:103], v[104:105], v[138:139] op_sel_hi:[1,0]
	v_cndmask_b32_e64 v104, 0, 1, s[12:13]
	v_pk_mul_f32 v[170:171], v[112:113], v[138:139] op_sel_hi:[1,0]
	v_pk_mul_f32 v[148:149], v[96:97], v[138:139] op_sel_hi:[1,0]
	v_pk_mul_f32 v[158:159], v[114:115], v[138:139] op_sel_hi:[1,0]
	v_pk_mul_f32 v[96:97], v[98:99], v[138:139] op_sel_hi:[1,0]
	v_pk_mul_f32 v[156:157], v[116:117], v[138:139] op_sel_hi:[1,0]
	v_pk_mul_f32 v[100:101], v[100:101], v[138:139] op_sel_hi:[1,0]
	v_pk_mul_f32 v[162:163], v[120:121], v[138:139] op_sel_hi:[1,0]
	v_pk_mul_f32 v[160:161], v[122:123], v[138:139] op_sel_hi:[1,0]
	v_pk_mul_f32 v[98:99], v[106:107], v[138:139] op_sel_hi:[1,0]
	v_pk_mul_f32 v[154:155], v[124:125], v[138:139] op_sel_hi:[1,0]
	v_pk_mul_f32 v[124:125], v[108:109], v[138:139] op_sel_hi:[1,0]
	v_pk_mul_f32 v[152:153], v[126:127], v[138:139] op_sel_hi:[1,0]
	v_pk_mul_f32 v[122:123], v[110:111], v[138:139] op_sel_hi:[1,0]
	v_cmp_ne_u32_e64 s[12:13], 1, v104
	s_cbranch_vccz .LBB0_149
	s_and_b64 vcc, exec, s[12:13]
	v_mov_b64_e32 v[106:107], v[170:171]
	v_mov_b64_e32 v[108:109], v[158:159]
	v_mov_b64_e32 v[110:111], v[156:157]
	v_mov_b64_e32 v[114:115], v[150:151]
	v_mov_b64_e32 v[138:139], v[148:149]
	v_mov_b64_e32 v[140:141], v[96:97]
	v_mov_b64_e32 v[142:143], v[100:101]
	v_mov_b64_e32 v[172:173], v[118:119]
	v_mov_b64_e32 v[112:113], v[162:163]
	v_mov_b64_e32 v[116:117], v[160:161]
	v_mov_b64_e32 v[120:121], v[154:155]
	v_mov_b64_e32 v[126:127], v[152:153]
	v_mov_b64_e32 v[144:145], v[102:103]
	v_mov_b64_e32 v[146:147], v[98:99]
	v_mov_b64_e32 v[174:175], v[124:125]
	v_mov_b64_e32 v[176:177], v[122:123]
	s_cbranch_vccnz .LBB0_148
	s_and_b64 vcc, exec, s[36:37]
	s_cbranch_vccz .LBB0_144
; DI void epi_gemm1(const Params& p, int l, const f32x16& a0, const f32x16& a1, int token, int trow, int cb, int h, char* wl) {
;     ...
;   } else {
; #pragma unroll
;     for (int nb = 0; nb < 2; ++nb)
; #pragma unroll
;       for (int i = 0; i < 16; ++i) { const float x = v[nb][i]; v[nb][i] = x * __builtin_amdgcn_rcpf(1.f + __builtin_amdgcn_exp2f(-LOG2E * x)); }
;   }
	v_mul_f32_e32 v104, 0xbfb8aa3b, v170
	v_mul_f32_e32 v105, 0xbfb8aa3b, v171
	v_exp_f32_e32 v104, v104
	v_exp_f32_e32 v105, v105
	v_mul_f32_e32 v106, 0xbfb8aa3b, v158
	v_exp_f32_e32 v108, v106
	v_add_f32_e32 v104, 1.0, v104
	v_add_f32_e32 v105, 1.0, v105
	v_mul_f32_e32 v106, 0xbfb8aa3b, v159
	v_rcp_f32_e32 v104, v104
	v_rcp_f32_e32 v105, v105
	v_exp_f32_e32 v109, v106
	v_mul_f32_e32 v145, 0xbfb8aa3b, v125
	v_exp_f32_e32 v145, v145
	v_pk_mul_f32 v[106:107], v[170:171], v[104:105]
	v_add_f32_e32 v104, 1.0, v108
	v_add_f32_e32 v105, 1.0, v109
	v_mul_f32_e32 v108, 0xbfb8aa3b, v156
	v_rcp_f32_e32 v104, v104
	v_rcp_f32_e32 v105, v105
	v_exp_f32_e32 v110, v108
	v_mul_f32_e32 v108, 0xbfb8aa3b, v157
	v_exp_f32_e32 v111, v108
	v_pk_mul_f32 v[108:109], v[158:159], v[104:105]
	v_add_f32_e32 v104, 1.0, v110
	v_mul_f32_e32 v110, 0xbfb8aa3b, v150
	v_add_f32_e32 v105, 1.0, v111
	v_exp_f32_e32 v112, v110
	v_mul_f32_e32 v110, 0xbfb8aa3b, v151
	v_rcp_f32_e32 v104, v104
	v_rcp_f32_e32 v105, v105
	v_exp_f32_e32 v113, v110
	s_mov_b64 s[6:7], 0
	v_pk_mul_f32 v[110:111], v[156:157], v[104:105]
	v_add_f32_e32 v104, 1.0, v112
	v_add_f32_e32 v105, 1.0, v113
	v_mul_f32_e32 v112, 0xbfb8aa3b, v162
	v_mul_f32_e32 v113, 0xbfb8aa3b, v163
	v_rcp_f32_e32 v104, v104
	v_rcp_f32_e32 v105, v105
	v_exp_f32_e32 v112, v112
	v_exp_f32_e32 v113, v113
	v_pk_mul_f32 v[114:115], v[150:151], v[104:105]
	v_add_f32_e32 v104, 1.0, v112
	v_add_f32_e32 v105, 1.0, v113
	v_mul_f32_e32 v112, 0xbfb8aa3b, v160
	v_rcp_f32_e32 v104, v104
	v_rcp_f32_e32 v105, v105
	v_exp_f32_e32 v116, v112
	v_mul_f32_e32 v112, 0xbfb8aa3b, v161
	v_exp_f32_e32 v117, v112
	v_pk_mul_f32 v[112:113], v[162:163], v[104:105]
	v_add_f32_e32 v104, 1.0, v116
	v_mul_f32_e32 v116, 0xbfb8aa3b, v154
	v_add_f32_e32 v105, 1.0, v117
	v_exp_f32_e32 v120, v116
	v_mul_f32_e32 v116, 0xbfb8aa3b, v155
	v_rcp_f32_e32 v104, v104
	v_rcp_f32_e32 v105, v105
	v_exp_f32_e32 v121, v116
	v_pk_mul_f32 v[116:117], v[160:161], v[104:105]
	v_add_f32_e32 v104, 1.0, v120
	v_add_f32_e32 v105, 1.0, v121
	v_mul_f32_e32 v120, 0xbfb8aa3b, v152
	v_rcp_f32_e32 v104, v104
	v_rcp_f32_e32 v105, v105
	v_exp_f32_e32 v126, v120
	v_mul_f32_e32 v120, 0xbfb8aa3b, v153
	v_exp_f32_e32 v127, v120
	v_pk_mul_f32 v[120:121], v[154:155], v[104:105]
	v_add_f32_e32 v104, 1.0, v126
	v_mul_f32_e32 v126, 0xbfb8aa3b, v148
	v_add_f32_e32 v105, 1.0, v127
	v_exp_f32_e32 v135, v126
	v_mul_f32_e32 v126, 0xbfb8aa3b, v149
	v_rcp_f32_e32 v104, v104
	v_rcp_f32_e32 v105, v105
	v_exp_f32_e32 v138, v126
	v_pk_mul_f32 v[126:127], v[152:153], v[104:105]
	v_add_f32_e32 v104, 1.0, v135
	v_add_f32_e32 v105, 1.0, v138
	v_mul_f32_e32 v135, 0xbfb8aa3b, v96
	v_mul_f32_e32 v138, 0xbfb8aa3b, v97
	v_rcp_f32_e32 v104, v104
	v_rcp_f32_e32 v105, v105
	v_exp_f32_e32 v135, v135
	v_exp_f32_e32 v140, v138
	v_pk_mul_f32 v[138:139], v[148:149], v[104:105]
	v_add_f32_e32 v104, 1.0, v135
	v_add_f32_e32 v105, 1.0, v140
	v_mul_f32_e32 v135, 0xbfb8aa3b, v100
	v_mul_f32_e32 v140, 0xbfb8aa3b, v101
	v_rcp_f32_e32 v104, v104
	v_rcp_f32_e32 v105, v105
	v_exp_f32_e32 v135, v135
	v_exp_f32_e32 v142, v140
	v_pk_mul_f32 v[140:141], v[96:97], v[104:105]
	v_add_f32_e32 v104, 1.0, v135
	v_add_f32_e32 v105, 1.0, v142
	v_mul_f32_e32 v135, 0xbfb8aa3b, v118
	v_mul_f32_e32 v142, 0xbfb8aa3b, v119
	v_rcp_f32_e32 v104, v104
	v_rcp_f32_e32 v105, v105
	v_exp_f32_e32 v135, v135
	v_exp_f32_e32 v144, v142
	v_pk_mul_f32 v[142:143], v[100:101], v[104:105]
	v_add_f32_e32 v104, 1.0, v135
	v_add_f32_e32 v105, 1.0, v144
	v_mul_f32_e32 v135, 0xbfb8aa3b, v102
	v_rcp_f32_e32 v104, v104
	v_rcp_f32_e32 v105, v105
	v_exp_f32_e32 v135, v135
	v_mul_f32_e32 v144, 0xbfb8aa3b, v103
	v_exp_f32_e32 v144, v144
	v_pk_mul_f32 v[172:173], v[118:119], v[104:105]
	v_add_f32_e32 v104, 1.0, v135
	v_mul_f32_e32 v135, 0xbfb8aa3b, v98
	v_add_f32_e32 v105, 1.0, v144
	v_exp_f32_e32 v135, v135
	v_mul_f32_e32 v144, 0xbfb8aa3b, v99
	v_exp_f32_e32 v144, v144
	v_rcp_f32_e32 v104, v104
	v_add_f32_e32 v135, 1.0, v135
	v_rcp_f32_e32 v146, v135
	v_add_f32_e32 v135, 1.0, v144
	v_mul_f32_e32 v144, 0xbfb8aa3b, v124
	v_exp_f32_e32 v144, v144
	v_rcp_f32_e32 v147, v135
	v_rcp_f32_e32 v105, v105
	v_add_f32_e32 v135, 1.0, v144
	v_mul_f32_e32 v144, 0xbfb8aa3b, v122
	v_rcp_f32_e32 v174, v135
	v_add_f32_e32 v135, 1.0, v145
	v_exp_f32_e32 v144, v144
	v_mul_f32_e32 v145, 0xbfb8aa3b, v123
	v_exp_f32_e32 v145, v145
	v_rcp_f32_e32 v175, v135
	v_add_f32_e32 v135, 1.0, v144
	v_rcp_f32_e32 v176, v135
	v_add_f32_e32 v135, 1.0, v145
	v_rcp_f32_e32 v177, v135
	v_pk_mul_f32 v[144:145], v[102:103], v[104:105]
	v_pk_mul_f32 v[146:147], v[98:99], v[146:147]
	v_pk_mul_f32 v[174:175], v[124:125], v[174:175]
	v_pk_mul_f32 v[176:177], v[122:123], v[176:177]

; DI void epi_gemm1(const Params& p, int l, const f32x16& a0, const f32x16& a1, int token, int trow, int cb, int h, char* wl) {
;     ...
;   const float rs = __builtin_amdgcn_rsqf(p.sumsq_x[l * T + token] * (1.f / 1024.f) + EPS);
;   float v[2][16];
; #pragma unroll
;   for (int i = 0; i < 16; ++i) { v[0][i] = a0[i] * rs; v[1][i] = a1[i] * rs; }
;     ...
; #pragma unroll
;   for (int nb = 0; nb < 2; ++nb)
; #pragma unroll
;     for (int g4 = 0; g4 < 4; ++g4)
;       stg4(wl, RS, trow, (nb * 32 + 8 * g4 + 4 * h) * 2, v[nb][4 * g4], v[nb][4 * g4 + 1], v[nb][4 * g4 + 2], v[nb][4 * g4 + 3]);
.LBB0_152:
	v_or_b32_e32 v148, 32, v134
	v_add_u32_e32 v96, s16, v148
	v_ashrrev_i32_e32 v97, 31, v96
	v_lshl_add_u64 v[96:97], v[96:97], 2, s[76:77]
	v_mov_b32_e32 v118, v216
	v_cvt_pk_bf16_f32 v98, v106, v107
	v_cvt_pk_bf16_f32 v99, v108, v109
	v_cvt_pk_bf16_f32 v100, v110, v111
	v_cvt_pk_bf16_f32 v101, v114, v115
	v_cvt_pk_bf16_f32 v102, v112, v113
	v_cvt_pk_bf16_f32 v103, v116, v117
	v_cvt_pk_bf16_f32 v106, v120, v121
	v_cvt_pk_bf16_f32 v107, v126, v127
	v_cvt_pk_bf16_f32 v108, v138, v139
	v_cvt_pk_bf16_f32 v109, v140, v141
	v_cvt_pk_bf16_f32 v110, v142, v143
	v_cvt_pk_bf16_f32 v111, v172, v173
	ds_write2_b64 v180, v[98:99], v[100:101] offset1:2
	ds_write2_b64 v180, v[102:103], v[106:107] offset0:4 offset1:6
	ds_write2_b64 v180, v[108:109], v[110:111] offset0:8 offset1:10
	v_cvt_pk_bf16_f32 v112, v144, v145
	v_cvt_pk_bf16_f32 v113, v146, v147
	v_cvt_pk_bf16_f32 v114, v174, v175
	v_cvt_pk_bf16_f32 v115, v176, v177
	s_andn2_b64 vcc, exec, s[72:73]
	s_mov_b64 s[72:73], -1
	ds_write2_b64 v180, v[112:113], v[114:115] offset0:12 offset1:14
	s_waitcnt vmcnt(0)
	v_fmamk_f32 v98, v118, 0x3a800000, v191
	v_rsq_f32_e32 v102, v98
	s_nop 0
	v_pk_mul_f32 v[140:141], v[80:81], v[102:103] op_sel_hi:[1,0]
	v_pk_mul_f32 v[110:111], v[64:65], v[102:103] op_sel_hi:[1,0]
	v_pk_mul_f32 v[124:125], v[82:83], v[102:103] op_sel_hi:[1,0]
	v_pk_mul_f32 v[64:65], v[66:67], v[102:103] op_sel_hi:[1,0]
	v_pk_mul_f32 v[122:123], v[84:85], v[102:103] op_sel_hi:[1,0]
	v_pk_mul_f32 v[108:109], v[68:69], v[102:103] op_sel_hi:[1,0]
	v_pk_mul_f32 v[116:117], v[86:87], v[102:103] op_sel_hi:[1,0]
	v_pk_mul_f32 v[98:99], v[70:71], v[102:103] op_sel_hi:[1,0]
	v_pk_mul_f32 v[138:139], v[88:89], v[102:103] op_sel_hi:[1,0]
	v_pk_mul_f32 v[70:71], v[72:73], v[102:103] op_sel_hi:[1,0]
	v_pk_mul_f32 v[126:127], v[90:91], v[102:103] op_sel_hi:[1,0]
	v_pk_mul_f32 v[66:67], v[74:75], v[102:103] op_sel_hi:[1,0]
	v_pk_mul_f32 v[120:121], v[92:93], v[102:103] op_sel_hi:[1,0]
	v_pk_mul_f32 v[100:101], v[76:77], v[102:103] op_sel_hi:[1,0]
	v_pk_mul_f32 v[118:119], v[94:95], v[102:103] op_sel_hi:[1,0]
	v_pk_mul_f32 v[94:95], v[78:79], v[102:103] op_sel_hi:[1,0]
	s_cbranch_vccnz .LBB0_161
	s_and_b64 vcc, exec, s[12:13]
	v_mov_b64_e32 v[72:73], v[140:141]
	v_mov_b64_e32 v[74:75], v[124:125]
	v_mov_b64_e32 v[76:77], v[122:123]
	v_mov_b64_e32 v[80:81], v[116:117]
	v_mov_b64_e32 v[88:89], v[110:111]
	v_mov_b64_e32 v[90:91], v[64:65]
	v_mov_b64_e32 v[92:93], v[108:109]
	v_mov_b64_e32 v[68:69], v[98:99]
	v_mov_b64_e32 v[78:79], v[138:139]
	v_mov_b64_e32 v[82:83], v[126:127]
	v_mov_b64_e32 v[84:85], v[120:121]
	v_mov_b64_e32 v[86:87], v[118:119]
	v_mov_b64_e32 v[102:103], v[70:71]
	v_mov_b64_e32 v[106:107], v[66:67]
	v_mov_b64_e32 v[112:113], v[100:101]
	v_mov_b64_e32 v[114:115], v[94:95]
	s_cbranch_vccnz .LBB0_160
	s_andn2_b64 vcc, exec, s[36:37]
	s_mov_b64 s[36:37], -1
	s_cbranch_vccnz .LBB0_156
; DI void epi_gemm1(const Params& p, int l, const f32x16& a0, const f32x16& a1, int token, int trow, int cb, int h, char* wl) {
;     ...
;   } else {
; #pragma unroll
;     for (int nb = 0; nb < 2; ++nb)
; #pragma unroll
;       for (int i = 0; i < 16; ++i) { const float x = v[nb][i]; v[nb][i] = x * __builtin_amdgcn_rcpf(1.f + __builtin_amdgcn_exp2f(-LOG2E * x)); }
;   }
	v_mul_f32_e32 v68, 0xbfb8aa3b, v140
	v_mul_f32_e32 v69, 0xbfb8aa3b, v141
	v_exp_f32_e32 v68, v68
	v_exp_f32_e32 v69, v69
	v_mul_f32_e32 v72, 0xbfb8aa3b, v124
	v_exp_f32_e32 v74, v72
	v_add_f32_e32 v68, 1.0, v68
	v_add_f32_e32 v69, 1.0, v69
	v_mul_f32_e32 v72, 0xbfb8aa3b, v125
	v_rcp_f32_e32 v68, v68
	v_rcp_f32_e32 v69, v69
	v_exp_f32_e32 v75, v72
	v_mul_f32_e32 v106, 0xbfb8aa3b, v66
	v_mul_f32_e32 v107, 0xbfb8aa3b, v67
	v_pk_mul_f32 v[72:73], v[140:141], v[68:69]
	v_add_f32_e32 v68, 1.0, v74
	v_add_f32_e32 v69, 1.0, v75
	v_mul_f32_e32 v74, 0xbfb8aa3b, v122
	v_rcp_f32_e32 v68, v68
	v_rcp_f32_e32 v69, v69
	v_exp_f32_e32 v76, v74
	v_mul_f32_e32 v74, 0xbfb8aa3b, v123
	v_exp_f32_e32 v77, v74
	v_pk_mul_f32 v[74:75], v[124:125], v[68:69]
	v_add_f32_e32 v68, 1.0, v76
	v_mul_f32_e32 v76, 0xbfb8aa3b, v116
	v_add_f32_e32 v69, 1.0, v77
	v_exp_f32_e32 v78, v76
	v_mul_f32_e32 v76, 0xbfb8aa3b, v117
	v_rcp_f32_e32 v68, v68
	v_rcp_f32_e32 v69, v69
	v_exp_f32_e32 v79, v76
	v_mul_f32_e32 v112, 0xbfb8aa3b, v100
	v_mul_f32_e32 v113, 0xbfb8aa3b, v101
	v_pk_mul_f32 v[76:77], v[122:123], v[68:69]
	v_add_f32_e32 v68, 1.0, v78
	v_add_f32_e32 v69, 1.0, v79
	v_mul_f32_e32 v78, 0xbfb8aa3b, v138
	v_rcp_f32_e32 v68, v68
	v_rcp_f32_e32 v69, v69
	v_exp_f32_e32 v78, v78
	v_mul_f32_e32 v79, 0xbfb8aa3b, v139
	v_exp_f32_e32 v79, v79
	v_pk_mul_f32 v[80:81], v[116:117], v[68:69]
	v_add_f32_e32 v68, 1.0, v78
	v_mul_f32_e32 v78, 0xbfb8aa3b, v126
	v_add_f32_e32 v69, 1.0, v79
	v_exp_f32_e32 v82, v78
	v_mul_f32_e32 v78, 0xbfb8aa3b, v127
	v_rcp_f32_e32 v68, v68
	v_rcp_f32_e32 v69, v69
	v_exp_f32_e32 v83, v78
	v_mul_f32_e32 v114, 0xbfb8aa3b, v94
	v_mul_f32_e32 v115, 0xbfb8aa3b, v95
	v_pk_mul_f32 v[78:79], v[138:139], v[68:69]
	v_add_f32_e32 v68, 1.0, v82
	v_add_f32_e32 v69, 1.0, v83
	v_mul_f32_e32 v82, 0xbfb8aa3b, v120
	v_rcp_f32_e32 v68, v68
	v_rcp_f32_e32 v69, v69
	v_exp_f32_e32 v84, v82
	v_mul_f32_e32 v82, 0xbfb8aa3b, v121
	v_exp_f32_e32 v85, v82
	v_pk_mul_f32 v[82:83], v[126:127], v[68:69]
	v_add_f32_e32 v68, 1.0, v84
	v_mul_f32_e32 v84, 0xbfb8aa3b, v118
	v_add_f32_e32 v69, 1.0, v85
	v_exp_f32_e32 v86, v84
	v_mul_f32_e32 v84, 0xbfb8aa3b, v119
	v_rcp_f32_e32 v68, v68
	v_rcp_f32_e32 v69, v69
	v_exp_f32_e32 v87, v84
	v_exp_f32_e32 v106, v106
	v_exp_f32_e32 v107, v107
	v_pk_mul_f32 v[84:85], v[120:121], v[68:69]
	v_add_f32_e32 v68, 1.0, v86
	v_add_f32_e32 v69, 1.0, v87
	v_mul_f32_e32 v86, 0xbfb8aa3b, v110
	v_rcp_f32_e32 v68, v68
	v_rcp_f32_e32 v69, v69
	v_exp_f32_e32 v88, v86
	v_mul_f32_e32 v86, 0xbfb8aa3b, v111
	v_exp_f32_e32 v89, v86
	v_pk_mul_f32 v[86:87], v[118:119], v[68:69]
	v_add_f32_e32 v68, 1.0, v88
	v_mul_f32_e32 v88, 0xbfb8aa3b, v64
	v_add_f32_e32 v69, 1.0, v89
	v_exp_f32_e32 v90, v88
	v_mul_f32_e32 v88, 0xbfb8aa3b, v65
	v_rcp_f32_e32 v68, v68
	v_rcp_f32_e32 v69, v69
	v_exp_f32_e32 v91, v88
	v_exp_f32_e32 v112, v112
	v_exp_f32_e32 v113, v113
	v_pk_mul_f32 v[88:89], v[110:111], v[68:69]
	v_add_f32_e32 v68, 1.0, v90
	v_add_f32_e32 v69, 1.0, v91
	v_mul_f32_e32 v90, 0xbfb8aa3b, v108
	v_rcp_f32_e32 v68, v68
	v_rcp_f32_e32 v69, v69
	v_exp_f32_e32 v92, v90
	v_mul_f32_e32 v90, 0xbfb8aa3b, v109
	v_exp_f32_e32 v93, v90
	v_pk_mul_f32 v[90:91], v[64:65], v[68:69]
	v_add_f32_e32 v68, 1.0, v92
	v_mul_f32_e32 v92, 0xbfb8aa3b, v98
	v_add_f32_e32 v69, 1.0, v93
	v_exp_f32_e32 v102, v92
	v_mul_f32_e32 v92, 0xbfb8aa3b, v99
	v_rcp_f32_e32 v68, v68
	v_rcp_f32_e32 v69, v69
	v_exp_f32_e32 v103, v92
	v_exp_f32_e32 v114, v114
	v_exp_f32_e32 v115, v115
	v_pk_mul_f32 v[92:93], v[108:109], v[68:69]
	v_add_f32_e32 v68, 1.0, v102
	v_add_f32_e32 v69, 1.0, v103
	v_mul_f32_e32 v102, 0xbfb8aa3b, v70
	v_mul_f32_e32 v103, 0xbfb8aa3b, v71
	v_exp_f32_e32 v102, v102
	v_exp_f32_e32 v103, v103
	v_add_f32_e32 v106, 1.0, v106
	v_add_f32_e32 v107, 1.0, v107
	v_add_f32_e32 v102, 1.0, v102
	v_add_f32_e32 v103, 1.0, v103
	v_add_f32_e32 v112, 1.0, v112
	v_add_f32_e32 v113, 1.0, v113
	v_add_f32_e32 v114, 1.0, v114
	v_add_f32_e32 v115, 1.0, v115
	v_rcp_f32_e32 v68, v68
	v_rcp_f32_e32 v69, v69
	v_rcp_f32_e32 v102, v102
	v_rcp_f32_e32 v103, v103
	v_rcp_f32_e32 v106, v106
	v_rcp_f32_e32 v107, v107
	v_rcp_f32_e32 v112, v112
	v_rcp_f32_e32 v113, v113
	v_rcp_f32_e32 v114, v114
	v_rcp_f32_e32 v115, v115
	v_pk_mul_f32 v[68:69], v[98:99], v[68:69]
	v_pk_mul_f32 v[102:103], v[70:71], v[102:103]
	v_pk_mul_f32 v[106:107], v[66:67], v[106:107]
	v_pk_mul_f32 v[112:113], v[100:101], v[112:113]
	v_pk_mul_f32 v[114:115], v[94:95], v[114:115]
	s_mov_b64 s[36:37], 0

; template <int CH>
; DI void flush_rows(const char* wl, int rs, int lane, char* dst0, size_t dstride) {
;   asm volatile("" : "+v"(lane));
; #pragma unroll
;   for (int j = 0; j < CH; ++j) {
;     const int idx = j * 64 + lane, row = idx / CH, ch = idx % CH;
;     const uint4 t = *(const uint4*)(wl + row * rs + ch * 16);
;     *(uint4*)(dst0 + (size_t)row * dstride + ch * 16) = t;
;   }
; }
; DI void epi_gemm1(const Params& p, int l, const f32x16& a0, const f32x16& a1, int token, int trow, int cb, int h, char* wl) {
;     ...
;   const float rs = __builtin_amdgcn_rsqf(p.sumsq_x[l * T + token] * (1.f / 1024.f) + EPS);
;   float v[2][16];
; #pragma unroll
;   for (int i = 0; i < 16; ++i) { v[0][i] = a0[i] * rs; v[1][i] = a1[i] * rs; }
.LBB0_204:
	v_mov_b32_e32 v78, v129
	s_movk_i32 s24, 0x90
	v_ashrrev_i32_e32 v64, 31, v78
	v_lshrrev_b32_e32 v64, 29, v64
	v_add_u32_e32 v64, v78, v64
	v_ashrrev_i32_e32 v70, 3, v64
	v_and_b32_e32 v64, 0xffffff8, v64
	v_sub_u32_e32 v64, v78, v64
	v_ashrrev_i32_e32 v71, 31, v70
	v_mov_b64_e32 v[72:73], s[14:15]
	v_mul_lo_u32 v65, v70, s24
	v_lshlrev_b32_e32 v68, 4, v64
	v_mul_lo_u32 v74, s2, v71
	v_mul_lo_u32 v75, s3, v70
	v_mad_u64_u32 v[70:71], s[14:15], s2, v70, v[72:73]
	v_ashrrev_i32_e32 v69, 31, v68
	v_add3_u32 v71, v75, v71, v74
	v_add3_u32 v64, s26, v65, v68
	v_lshl_add_u64 v[74:75], v[70:71], 0, v[68:69]
	v_add_u32_e32 v68, 64, v78
	v_ashrrev_i32_e32 v69, 31, v68
	v_lshrrev_b32_e32 v69, 29, v69
	v_add_u32_e32 v69, v68, v69
	ds_read_b128 v[64:67], v64
	v_ashrrev_i32_e32 v79, 3, v69
	v_and_b32_e32 v69, 0xffffff8, v69
	v_sub_u32_e32 v68, v68, v69
	v_mul_lo_u32 v69, v79, s24
	v_lshlrev_b32_e32 v76, 4, v68
	v_add3_u32 v68, s26, v69, v76
	ds_read_b128 v[68:71], v68
	s_waitcnt lgkmcnt(1)
	global_store_dwordx4 v[74:75], v[64:67], off
	v_ashrrev_i32_e32 v77, 31, v76
	s_mov_b64 s[72:73], -1
	v_ashrrev_i32_e32 v64, 31, v79
	v_mul_lo_u32 v66, s2, v64
	v_mul_lo_u32 v67, s3, v79
	v_mad_u64_u32 v[64:65], s[14:15], s2, v79, v[72:73]
	v_add3_u32 v65, v67, v65, v66
	v_lshl_add_u64 v[64:65], v[64:65], 0, v[76:77]
	s_waitcnt lgkmcnt(0)
	global_store_dwordx4 v[64:65], v[68:71], off
	v_add_u32_e32 v64, 0x80, v78
	v_ashrrev_i32_e32 v65, 31, v64
	v_lshrrev_b32_e32 v65, 29, v65
	v_add_u32_e32 v65, v64, v65
	v_ashrrev_i32_e32 v70, 3, v65
	v_and_b32_e32 v65, 0xffffff8, v65
	v_sub_u32_e32 v64, v64, v65
	v_ashrrev_i32_e32 v71, 31, v70
	v_mul_lo_u32 v65, v70, s24
	v_lshlrev_b32_e32 v68, 4, v64
	v_mul_lo_u32 v74, s2, v71
	v_mul_lo_u32 v75, s3, v70
	v_mad_u64_u32 v[70:71], s[14:15], s2, v70, v[72:73]
	v_ashrrev_i32_e32 v69, 31, v68
	v_add3_u32 v71, v75, v71, v74
	v_add3_u32 v64, s26, v65, v68
	v_lshl_add_u64 v[74:75], v[70:71], 0, v[68:69]
	v_add_u32_e32 v68, 0xc0, v78
	v_ashrrev_i32_e32 v69, 31, v68
	v_lshrrev_b32_e32 v69, 29, v69
	v_add_u32_e32 v69, v68, v69
	ds_read_b128 v[64:67], v64
	v_ashrrev_i32_e32 v79, 3, v69
	v_and_b32_e32 v69, 0xffffff8, v69
	v_sub_u32_e32 v68, v68, v69
	v_mul_lo_u32 v69, v79, s24
	v_lshlrev_b32_e32 v76, 4, v68
	v_add3_u32 v68, s26, v69, v76
	ds_read_b128 v[68:71], v68
	s_waitcnt lgkmcnt(1)
	global_store_dwordx4 v[74:75], v[64:67], off
	v_ashrrev_i32_e32 v77, 31, v76
	s_nop 0
	v_ashrrev_i32_e32 v64, 31, v79
	v_mul_lo_u32 v66, s2, v64
	v_mul_lo_u32 v67, s3, v79
	v_mad_u64_u32 v[64:65], s[14:15], s2, v79, v[72:73]
	v_add3_u32 v65, v67, v65, v66
	v_lshl_add_u64 v[64:65], v[64:65], 0, v[76:77]
	s_waitcnt lgkmcnt(0)
	global_store_dwordx4 v[64:65], v[68:71], off
	v_add_u32_e32 v64, 0x100, v78
	v_ashrrev_i32_e32 v65, 31, v64
	v_lshrrev_b32_e32 v65, 29, v65
	v_add_u32_e32 v65, v64, v65
	v_ashrrev_i32_e32 v70, 3, v65
	v_and_b32_e32 v65, 0xffffff8, v65
	v_sub_u32_e32 v64, v64, v65
	v_ashrrev_i32_e32 v71, 31, v70
	v_mul_lo_u32 v65, v70, s24
	v_lshlrev_b32_e32 v68, 4, v64
	v_mul_lo_u32 v74, s2, v71
	v_mul_lo_u32 v75, s3, v70
	v_mad_u64_u32 v[70:71], s[14:15], s2, v70, v[72:73]
	v_ashrrev_i32_e32 v69, 31, v68
	v_add3_u32 v71, v75, v71, v74
	v_add3_u32 v64, s26, v65, v68
	v_lshl_add_u64 v[74:75], v[70:71], 0, v[68:69]
	v_add_u32_e32 v68, 0x140, v78
	v_ashrrev_i32_e32 v69, 31, v68
	v_lshrrev_b32_e32 v69, 29, v69
	v_add_u32_e32 v69, v68, v69
	ds_read_b128 v[64:67], v64
	v_ashrrev_i32_e32 v79, 3, v69
	v_and_b32_e32 v69, 0xffffff8, v69
	v_sub_u32_e32 v68, v68, v69
	v_mul_lo_u32 v69, v79, s24
	v_lshlrev_b32_e32 v76, 4, v68
	v_add3_u32 v68, s26, v69, v76
	ds_read_b128 v[68:71], v68
	s_waitcnt lgkmcnt(1)
	global_store_dwordx4 v[74:75], v[64:67], off
	v_ashrrev_i32_e32 v77, 31, v76
	s_nop 0
	v_ashrrev_i32_e32 v64, 31, v79
	v_mul_lo_u32 v66, s2, v64
	v_mul_lo_u32 v67, s3, v79
	v_mad_u64_u32 v[64:65], s[14:15], s2, v79, v[72:73]
	v_add3_u32 v65, v67, v65, v66
	v_lshl_add_u64 v[64:65], v[64:65], 0, v[76:77]
	s_waitcnt lgkmcnt(0)
	global_store_dwordx4 v[64:65], v[68:71], off
	v_add_u32_e32 v64, 0x180, v78
	v_ashrrev_i32_e32 v65, 31, v64
	v_lshrrev_b32_e32 v65, 29, v65
	v_add_u32_e32 v65, v64, v65
	v_ashrrev_i32_e32 v70, 3, v65
	v_and_b32_e32 v65, 0xffffff8, v65
	v_sub_u32_e32 v64, v64, v65
	v_ashrrev_i32_e32 v71, 31, v70
	v_mul_lo_u32 v65, v70, s24
	v_lshlrev_b32_e32 v68, 4, v64
	v_mul_lo_u32 v74, s2, v71
	v_mul_lo_u32 v75, s3, v70
	v_mad_u64_u32 v[70:71], s[14:15], s2, v70, v[72:73]
	v_ashrrev_i32_e32 v69, 31, v68
	v_add3_u32 v71, v75, v71, v74
	v_add3_u32 v64, s26, v65, v68
	v_lshl_add_u64 v[74:75], v[70:71], 0, v[68:69]
	v_add_u32_e32 v68, 0x1c0, v78
	v_ashrrev_i32_e32 v69, 31, v68
	v_lshrrev_b32_e32 v69, 29, v69
	v_add_u32_e32 v69, v68, v69
	ds_read_b128 v[64:67], v64
	v_ashrrev_i32_e32 v78, 3, v69
	v_and_b32_e32 v69, 0xffffff8, v69
	v_sub_u32_e32 v68, v68, v69
	v_mul_lo_u32 v69, v78, s24
	v_lshlrev_b32_e32 v76, 4, v68
	v_add3_u32 v68, s26, v69, v76
	ds_read_b128 v[68:71], v68
	s_waitcnt lgkmcnt(1)
	global_store_dwordx4 v[74:75], v[64:67], off
	v_ashrrev_i32_e32 v77, 31, v76
	s_nop 0
	v_ashrrev_i32_e32 v64, 31, v78
	v_mul_lo_u32 v66, s2, v64
	v_mul_lo_u32 v67, s3, v78
	v_mad_u64_u32 v[64:65], s[2:3], s2, v78, v[72:73]
	v_add3_u32 v65, v67, v65, v66
	v_lshl_add_u64 v[64:65], v[64:65], 0, v[76:77]
	s_waitcnt lgkmcnt(0)
	global_store_dwordx4 v[64:65], v[68:71], off
	global_load_dword v64, v[136:137], off
	global_load_dword v216, v[136:137], off offset:128
	v_readlane_b32 s2, v255, 51
	s_or_b32 s24, s97, s2
	s_add_i32 s87, s24, 0xfffff900
	s_cmpk_lt_u32 s87, 0x200
	s_cselect_b64 s[2:3], -1, 0
	s_or_b64 s[36:37], s[8:9], s[2:3]
	s_add_i32 s2, s24, 0xfffffc00
	s_cmpk_gt_u32 s2, 0x17f
	s_cselect_b64 s[34:35], -1, 0
	s_cmpk_lt_u32 s24, 0x880
	s_cselect_b64 s[14:15], -1, 0
	s_cmpk_gt_u32 s24, 0x87f
	s_cselect_b64 s[2:3], -1, 0
	s_and_b64 vcc, exec, s[36:37]
	s_waitcnt vmcnt(0)
	v_fmamk_f32 v64, v64, 0x3a800000, v191
	v_rsq_f32_e32 v66, v64
	s_nop 0
	v_pk_mul_f32 v[90:91], v[48:49], v[66:67] op_sel_hi:[1,0]
	v_pk_mul_f32 v[70:71], v[32:33], v[66:67] op_sel_hi:[1,0]
	v_pk_mul_f32 v[86:87], v[50:51], v[66:67] op_sel_hi:[1,0]
	v_pk_mul_f32 v[34:35], v[34:35], v[66:67] op_sel_hi:[1,0]
	v_pk_mul_f32 v[78:79], v[52:53], v[66:67] op_sel_hi:[1,0]
	v_pk_mul_f32 v[36:37], v[36:37], v[66:67] op_sel_hi:[1,0]
	v_pk_mul_f32 v[76:77], v[54:55], v[66:67] op_sel_hi:[1,0]
	v_pk_mul_f32 v[64:65], v[38:39], v[66:67] op_sel_hi:[1,0]
	v_pk_mul_f32 v[92:93], v[56:57], v[66:67] op_sel_hi:[1,0]
	v_pk_mul_f32 v[38:39], v[40:41], v[66:67] op_sel_hi:[1,0]
	v_pk_mul_f32 v[94:95], v[58:59], v[66:67] op_sel_hi:[1,0]
	v_pk_mul_f32 v[74:75], v[42:43], v[66:67] op_sel_hi:[1,0]
	v_pk_mul_f32 v[80:81], v[60:61], v[66:67] op_sel_hi:[1,0]
	v_pk_mul_f32 v[60:61], v[44:45], v[66:67] op_sel_hi:[1,0]
	v_pk_mul_f32 v[82:83], v[62:63], v[66:67] op_sel_hi:[1,0]
	v_pk_mul_f32 v[62:63], v[46:47], v[66:67] op_sel_hi:[1,0]
	s_cbranch_vccnz .LBB0_213
; DI void epi_gemm1(const Params& p, int l, const f32x16& a0, const f32x16& a1, int token, int trow, int cb, int h, char* wl) {
;     ...
;   } else {
; #pragma unroll
;     for (int nb = 0; nb < 2; ++nb)
; #pragma unroll
;       for (int i = 0; i < 16; ++i) { const float x = v[nb][i]; v[nb][i] = x * __builtin_amdgcn_rcpf(1.f + __builtin_amdgcn_exp2f(-LOG2E * x)); }
;   }
	s_and_b64 vcc, exec, s[12:13]
	v_mov_b64_e32 v[40:41], v[90:91]
	v_mov_b64_e32 v[42:43], v[86:87]
	v_mov_b64_e32 v[44:45], v[78:79]
	v_mov_b64_e32 v[48:49], v[76:77]
	v_mov_b64_e32 v[56:57], v[70:71]
	v_mov_b64_e32 v[58:59], v[34:35]
	v_mov_b64_e32 v[32:33], v[36:37]
	v_mov_b64_e32 v[72:73], v[64:65]
	v_mov_b64_e32 v[46:47], v[92:93]
	v_mov_b64_e32 v[50:51], v[94:95]
	v_mov_b64_e32 v[52:53], v[80:81]
	v_mov_b64_e32 v[54:55], v[82:83]
	v_mov_b64_e32 v[66:67], v[38:39]
	v_mov_b64_e32 v[68:69], v[74:75]
	v_mov_b64_e32 v[84:85], v[60:61]
	v_mov_b64_e32 v[88:89], v[62:63]
	s_cbranch_vccnz .LBB0_212
	s_andn2_b64 vcc, exec, s[34:35]
	s_cbranch_vccnz .LBB0_208
	v_mul_f32_e32 v32, 0xbfb8aa3b, v90
	v_mul_f32_e32 v33, 0xbfb8aa3b, v91
	v_exp_f32_e32 v32, v32
	v_exp_f32_e32 v33, v33
	v_mul_f32_e32 v40, 0xbfb8aa3b, v86
	v_exp_f32_e32 v42, v40
	v_add_f32_e32 v32, 1.0, v32
	v_add_f32_e32 v33, 1.0, v33
	v_mul_f32_e32 v40, 0xbfb8aa3b, v87
	v_rcp_f32_e32 v32, v32
	v_rcp_f32_e32 v33, v33
	v_exp_f32_e32 v43, v40
	v_mul_f32_e32 v68, 0xbfb8aa3b, v38
	v_mul_f32_e32 v69, 0xbfb8aa3b, v39
	v_pk_mul_f32 v[40:41], v[90:91], v[32:33]
	v_add_f32_e32 v32, 1.0, v42
	v_add_f32_e32 v33, 1.0, v43
	v_mul_f32_e32 v42, 0xbfb8aa3b, v78
	v_rcp_f32_e32 v32, v32
	v_rcp_f32_e32 v33, v33
	v_exp_f32_e32 v44, v42
	v_mul_f32_e32 v42, 0xbfb8aa3b, v79
	v_exp_f32_e32 v45, v42
	v_pk_mul_f32 v[42:43], v[86:87], v[32:33]
	v_add_f32_e32 v32, 1.0, v44
	v_mul_f32_e32 v44, 0xbfb8aa3b, v76
	v_add_f32_e32 v33, 1.0, v45
	v_exp_f32_e32 v46, v44
	v_mul_f32_e32 v44, 0xbfb8aa3b, v77
	v_rcp_f32_e32 v32, v32
	v_rcp_f32_e32 v33, v33
	v_exp_f32_e32 v47, v44
	v_exp_f32_e32 v68, v68
	v_exp_f32_e32 v69, v69
	v_pk_mul_f32 v[44:45], v[78:79], v[32:33]
	v_add_f32_e32 v32, 1.0, v46
	v_add_f32_e32 v33, 1.0, v47
	v_mul_f32_e32 v46, 0xbfb8aa3b, v92
	v_mul_f32_e32 v47, 0xbfb8aa3b, v93
	v_rcp_f32_e32 v32, v32
	v_rcp_f32_e32 v33, v33
	v_exp_f32_e32 v46, v46
	v_exp_f32_e32 v47, v47
	v_mul_f32_e32 v84, 0xbfb8aa3b, v60
	v_pk_mul_f32 v[48:49], v[76:77], v[32:33]
	v_add_f32_e32 v32, 1.0, v46
	v_add_f32_e32 v33, 1.0, v47
	v_mul_f32_e32 v46, 0xbfb8aa3b, v94
	v_rcp_f32_e32 v32, v32
	v_rcp_f32_e32 v33, v33
	v_exp_f32_e32 v50, v46
	v_mul_f32_e32 v46, 0xbfb8aa3b, v95
	v_exp_f32_e32 v51, v46
	v_pk_mul_f32 v[46:47], v[92:93], v[32:33]
	v_add_f32_e32 v32, 1.0, v50
	v_mul_f32_e32 v50, 0xbfb8aa3b, v80
	v_add_f32_e32 v33, 1.0, v51
	v_exp_f32_e32 v52, v50
	v_mul_f32_e32 v50, 0xbfb8aa3b, v81
	v_rcp_f32_e32 v32, v32
	v_rcp_f32_e32 v33, v33
	v_exp_f32_e32 v53, v50
	v_mul_f32_e32 v85, 0xbfb8aa3b, v61
	v_mul_f32_e32 v88, 0xbfb8aa3b, v62
	v_pk_mul_f32 v[50:51], v[94:95], v[32:33]
	v_add_f32_e32 v32, 1.0, v52
	v_add_f32_e32 v33, 1.0, v53
	v_mul_f32_e32 v52, 0xbfb8aa3b, v82
	v_rcp_f32_e32 v32, v32
	v_rcp_f32_e32 v33, v33
	v_exp_f32_e32 v54, v52
	v_mul_f32_e32 v52, 0xbfb8aa3b, v83
	v_exp_f32_e32 v55, v52
	v_pk_mul_f32 v[52:53], v[80:81], v[32:33]
	v_add_f32_e32 v32, 1.0, v54
	v_mul_f32_e32 v54, 0xbfb8aa3b, v70
	v_add_f32_e32 v33, 1.0, v55
	v_exp_f32_e32 v56, v54
	v_mul_f32_e32 v54, 0xbfb8aa3b, v71
	v_rcp_f32_e32 v32, v32
	v_rcp_f32_e32 v33, v33
	v_exp_f32_e32 v57, v54
	v_mul_f32_e32 v89, 0xbfb8aa3b, v63
	v_exp_f32_e32 v84, v84
	v_pk_mul_f32 v[54:55], v[82:83], v[32:33]
	v_add_f32_e32 v32, 1.0, v56
	v_add_f32_e32 v33, 1.0, v57
	v_mul_f32_e32 v56, 0xbfb8aa3b, v34
	v_rcp_f32_e32 v32, v32
	v_rcp_f32_e32 v33, v33
	v_exp_f32_e32 v58, v56
	v_mul_f32_e32 v56, 0xbfb8aa3b, v35
	v_exp_f32_e32 v59, v56
	v_pk_mul_f32 v[56:57], v[70:71], v[32:33]
	v_add_f32_e32 v32, 1.0, v58
	v_mul_f32_e32 v58, 0xbfb8aa3b, v36
	v_add_f32_e32 v33, 1.0, v59
	v_exp_f32_e32 v66, v58
	v_mul_f32_e32 v58, 0xbfb8aa3b, v37
	v_rcp_f32_e32 v32, v32
	v_rcp_f32_e32 v33, v33
	v_exp_f32_e32 v67, v58
	v_exp_f32_e32 v85, v85
	v_exp_f32_e32 v88, v88
	v_pk_mul_f32 v[58:59], v[34:35], v[32:33]
	v_add_f32_e32 v32, 1.0, v66
	v_add_f32_e32 v33, 1.0, v67
	v_mul_f32_e32 v66, 0xbfb8aa3b, v64
	v_mul_f32_e32 v67, 0xbfb8aa3b, v65
	v_exp_f32_e32 v66, v66
	v_exp_f32_e32 v67, v67
	v_exp_f32_e32 v89, v89
	v_add_f32_e32 v84, 1.0, v84
	v_add_f32_e32 v66, 1.0, v66
	v_add_f32_e32 v67, 1.0, v67
	v_rcp_f32_e32 v66, v66
	v_rcp_f32_e32 v67, v67
	v_add_f32_e32 v85, 1.0, v85
	v_add_f32_e32 v88, 1.0, v88
	v_add_f32_e32 v89, 1.0, v89
	v_pk_mul_f32 v[72:73], v[64:65], v[66:67]
	v_add_f32_e32 v66, 1.0, v68
	v_add_f32_e32 v67, 1.0, v69
	v_mul_f32_e32 v68, 0xbfb8aa3b, v74
	v_mul_f32_e32 v69, 0xbfb8aa3b, v75
	v_exp_f32_e32 v68, v68
	v_exp_f32_e32 v69, v69
	v_rcp_f32_e32 v32, v32
	v_rcp_f32_e32 v33, v33
	v_add_f32_e32 v68, 1.0, v68
	v_add_f32_e32 v69, 1.0, v69
	v_rcp_f32_e32 v66, v66
	v_rcp_f32_e32 v67, v67
	v_rcp_f32_e32 v68, v68
	v_rcp_f32_e32 v69, v69
	v_rcp_f32_e32 v84, v84
	v_rcp_f32_e32 v85, v85
	v_rcp_f32_e32 v88, v88
	v_rcp_f32_e32 v89, v89
	v_pk_mul_f32 v[32:33], v[36:37], v[32:33]
	v_pk_mul_f32 v[66:67], v[38:39], v[66:67]
	v_pk_mul_f32 v[68:69], v[74:75], v[68:69]
	v_pk_mul_f32 v[84:85], v[60:61], v[84:85]
	v_pk_mul_f32 v[88:89], v[62:63], v[88:89]
	s_mov_b64 s[72:73], 0

; DI void epi_gemm1(const Params& p, int l, const f32x16& a0, const f32x16& a1, int token, int trow, int cb, int h, char* wl) {
;   constexpr int RS = 144;
;   const int sp = token & 8191;
;   const float rs = __builtin_amdgcn_rsqf(p.sumsq_x[l * T + token] * (1.f / 1024.f) + EPS);
;   float v[2][16];
; #pragma unroll
;   for (int i = 0; i < 16; ++i) { v[0][i] = a0[i] * rs; v[1][i] = a1[i] * rs; }
;     ...
;   } else {
; #pragma unroll
;     for (int nb = 0; nb < 2; ++nb)
; #pragma unroll
;       for (int i = 0; i < 16; ++i) { const float x = v[nb][i]; v[nb][i] = x * __builtin_amdgcn_rcpf(1.f + __builtin_amdgcn_exp2f(-LOG2E * x)); }
;   }
; #pragma unroll
;   for (int nb = 0; nb < 2; ++nb)
; #pragma unroll
;     for (int g4 = 0; g4 < 4; ++g4)
;       stg4(wl, RS, trow, (nb * 32 + 8 * g4 + 4 * h) * 2, v[nb][4 * g4], v[nb][4 * g4 + 1], v[nb][4 * g4 + 2], v[nb][4 * g4 + 3]);
.LBB0_217:
	v_mov_b32_e32 v60, v216
	v_cvt_pk_bf16_f32 v34, v40, v41
	v_cvt_pk_bf16_f32 v35, v42, v43
	v_cvt_pk_bf16_f32 v36, v44, v45
	v_cvt_pk_bf16_f32 v37, v48, v49
	v_cvt_pk_bf16_f32 v32, v32, v33
	v_cvt_pk_bf16_f32 v38, v46, v47
	v_cvt_pk_bf16_f32 v39, v50, v51
	v_cvt_pk_bf16_f32 v40, v52, v53
	v_cvt_pk_bf16_f32 v41, v54, v55
	v_cvt_pk_bf16_f32 v42, v56, v57
	v_cvt_pk_bf16_f32 v43, v58, v59
	v_cvt_pk_bf16_f32 v33, v72, v73
	ds_write2_b64 v180, v[34:35], v[36:37] offset1:2
	ds_write2_b64 v180, v[38:39], v[40:41] offset0:4 offset1:6
	ds_write2_b64 v180, v[42:43], v[32:33] offset0:8 offset1:10
	v_cvt_pk_bf16_f32 v44, v66, v67
	v_cvt_pk_bf16_f32 v45, v68, v69
	v_cvt_pk_bf16_f32 v46, v84, v85
	v_cvt_pk_bf16_f32 v47, v88, v89
	s_xor_b64 s[36:37], s[36:37], -1
	ds_write2_b64 v180, v[44:45], v[46:47] offset0:12 offset1:14
	s_andn2_b64 vcc, exec, s[36:37]
	s_mov_b64 s[36:37], -1
	s_mov_b32 s73, 0xdb629599
	s_waitcnt vmcnt(0)
	v_fmamk_f32 v32, v60, 0x3a800000, v191
	v_rsq_f32_e32 v36, v32
	s_nop 0
	v_pk_mul_f32 v[62:63], v[16:17], v[36:37] op_sel_hi:[1,0]
	v_pk_mul_f32 v[42:43], v[0:1], v[36:37] op_sel_hi:[1,0]
	v_pk_mul_f32 v[56:57], v[18:19], v[36:37] op_sel_hi:[1,0]
	v_pk_mul_f32 v[0:1], v[2:3], v[36:37] op_sel_hi:[1,0]
	v_pk_mul_f32 v[50:51], v[20:21], v[36:37] op_sel_hi:[1,0]
	v_pk_mul_f32 v[4:5], v[4:5], v[36:37] op_sel_hi:[1,0]
	v_pk_mul_f32 v[44:45], v[22:23], v[36:37] op_sel_hi:[1,0]
	v_pk_mul_f32 v[32:33], v[6:7], v[36:37] op_sel_hi:[1,0]
	v_pk_mul_f32 v[60:61], v[24:25], v[36:37] op_sel_hi:[1,0]
	v_pk_mul_f32 v[6:7], v[8:9], v[36:37] op_sel_hi:[1,0]
	v_pk_mul_f32 v[58:59], v[26:27], v[36:37] op_sel_hi:[1,0]
	v_pk_mul_f32 v[2:3], v[10:11], v[36:37] op_sel_hi:[1,0]
	v_pk_mul_f32 v[48:49], v[28:29], v[36:37] op_sel_hi:[1,0]
	v_pk_mul_f32 v[34:35], v[12:13], v[36:37] op_sel_hi:[1,0]
	v_pk_mul_f32 v[46:47], v[30:31], v[36:37] op_sel_hi:[1,0]
	v_pk_mul_f32 v[28:29], v[14:15], v[36:37] op_sel_hi:[1,0]
	s_cbranch_vccnz .LBB0_226
	s_and_b64 vcc, exec, s[12:13]
	v_mov_b64_e32 v[8:9], v[62:63]
	v_mov_b64_e32 v[10:11], v[56:57]
	v_mov_b64_e32 v[12:13], v[50:51]
	v_mov_b64_e32 v[16:17], v[44:45]
	v_mov_b64_e32 v[24:25], v[42:43]
	v_mov_b64_e32 v[26:27], v[0:1]
	v_mov_b64_e32 v[30:31], v[4:5]
	v_mov_b64_e32 v[40:41], v[32:33]
	v_mov_b64_e32 v[14:15], v[60:61]
	v_mov_b64_e32 v[18:19], v[58:59]
	v_mov_b64_e32 v[20:21], v[48:49]
	v_mov_b64_e32 v[22:23], v[46:47]
	v_mov_b64_e32 v[36:37], v[6:7]
	v_mov_b64_e32 v[38:39], v[2:3]
	v_mov_b64_e32 v[52:53], v[34:35]
	v_mov_b64_e32 v[54:55], v[28:29]
	s_cbranch_vccnz .LBB0_225
	s_andn2_b64 vcc, exec, s[34:35]
	s_mov_b64 s[12:13], -1
	s_cbranch_vccnz .LBB0_221
	v_mul_f32_e32 v14, 0xbfb8aa3b, v44
	v_mul_f32_e32 v15, 0xbfb8aa3b, v45
	v_mul_f32_e32 v36, 0xbfb8aa3b, v32
	v_mul_f32_e32 v37, 0xbfb8aa3b, v33
	v_exp_f32_e32 v14, v14
	v_exp_f32_e32 v15, v15
	v_exp_f32_e32 v36, v36
	v_exp_f32_e32 v37, v37
	v_mul_f32_e32 v16, 0xbfb8aa3b, v60
	v_add_f32_e32 v14, 1.0, v14
	v_add_f32_e32 v15, 1.0, v15
	v_exp_f32_e32 v18, v16
	v_mul_f32_e32 v16, 0xbfb8aa3b, v61
	v_add_f32_e32 v36, 1.0, v36
	v_add_f32_e32 v37, 1.0, v37
	v_mul_f32_e32 v38, 0xbfb8aa3b, v6
	v_mul_f32_e32 v39, 0xbfb8aa3b, v7
	v_rcp_f32_e32 v14, v14
	v_rcp_f32_e32 v15, v15
	v_exp_f32_e32 v19, v16
	v_rcp_f32_e32 v36, v36
	v_rcp_f32_e32 v37, v37
	v_exp_f32_e32 v38, v38
	v_exp_f32_e32 v39, v39
	v_mul_f32_e32 v8, 0xbfb8aa3b, v62
	v_mul_f32_e32 v9, 0xbfb8aa3b, v63
	v_mul_f32_e32 v10, 0xbfb8aa3b, v56
	v_mul_f32_e32 v11, 0xbfb8aa3b, v57
	v_mul_f32_e32 v12, 0xbfb8aa3b, v50
	v_mul_f32_e32 v13, 0xbfb8aa3b, v51
	v_pk_mul_f32 v[16:17], v[44:45], v[14:15]
	v_add_f32_e32 v14, 1.0, v18
	v_add_f32_e32 v15, 1.0, v19
	v_mul_f32_e32 v18, 0xbfb8aa3b, v58
	v_mul_f32_e32 v19, 0xbfb8aa3b, v59
	v_mul_f32_e32 v20, 0xbfb8aa3b, v48
	v_mul_f32_e32 v21, 0xbfb8aa3b, v49
	v_mul_f32_e32 v22, 0xbfb8aa3b, v46
	v_mul_f32_e32 v23, 0xbfb8aa3b, v47
	v_mul_f32_e32 v24, 0xbfb8aa3b, v42
	v_mul_f32_e32 v25, 0xbfb8aa3b, v43
	v_mul_f32_e32 v26, 0xbfb8aa3b, v0
	v_mul_f32_e32 v27, 0xbfb8aa3b, v1
	v_mul_f32_e32 v30, 0xbfb8aa3b, v4
	v_mul_f32_e32 v31, 0xbfb8aa3b, v5
	v_pk_mul_f32 v[40:41], v[32:33], v[36:37]
	v_add_f32_e32 v36, 1.0, v38
	v_add_f32_e32 v37, 1.0, v39
	v_mul_f32_e32 v38, 0xbfb8aa3b, v2
	v_mul_f32_e32 v39, 0xbfb8aa3b, v3
	v_mul_f32_e32 v52, 0xbfb8aa3b, v34
	v_mul_f32_e32 v53, 0xbfb8aa3b, v35
	v_mul_f32_e32 v54, 0xbfb8aa3b, v28
	v_mul_f32_e32 v55, 0xbfb8aa3b, v29
	v_exp_f32_e32 v8, v8
	v_exp_f32_e32 v9, v9
	v_exp_f32_e32 v10, v10
	v_exp_f32_e32 v11, v11
	v_exp_f32_e32 v12, v12
	v_exp_f32_e32 v13, v13
	v_exp_f32_e32 v18, v18
	v_exp_f32_e32 v19, v19
	v_exp_f32_e32 v20, v20
	v_exp_f32_e32 v21, v21
	v_exp_f32_e32 v22, v22
	v_exp_f32_e32 v23, v23
	v_exp_f32_e32 v24, v24
	v_exp_f32_e32 v25, v25
	v_exp_f32_e32 v26, v26
	v_exp_f32_e32 v27, v27
	v_exp_f32_e32 v30, v30
	v_exp_f32_e32 v31, v31
	v_exp_f32_e32 v38, v38
	v_exp_f32_e32 v39, v39
	v_exp_f32_e32 v52, v52
	v_exp_f32_e32 v53, v53
	v_exp_f32_e32 v54, v54
	v_exp_f32_e32 v55, v55
	v_add_f32_e32 v8, 1.0, v8
	v_add_f32_e32 v9, 1.0, v9
	v_add_f32_e32 v10, 1.0, v10
	v_add_f32_e32 v11, 1.0, v11
	v_add_f32_e32 v12, 1.0, v12
	v_add_f32_e32 v13, 1.0, v13
	v_add_f32_e32 v18, 1.0, v18
	v_add_f32_e32 v19, 1.0, v19
	v_add_f32_e32 v20, 1.0, v20
	v_add_f32_e32 v21, 1.0, v21
	v_add_f32_e32 v22, 1.0, v22
	v_add_f32_e32 v23, 1.0, v23
	v_add_f32_e32 v24, 1.0, v24
	v_add_f32_e32 v25, 1.0, v25
	v_add_f32_e32 v26, 1.0, v26
	v_add_f32_e32 v27, 1.0, v27
	v_add_f32_e32 v30, 1.0, v30
	v_add_f32_e32 v31, 1.0, v31
	v_add_f32_e32 v38, 1.0, v38
	v_add_f32_e32 v39, 1.0, v39
	v_add_f32_e32 v52, 1.0, v52
	v_add_f32_e32 v53, 1.0, v53
	v_add_f32_e32 v54, 1.0, v54
	v_add_f32_e32 v55, 1.0, v55
	v_rcp_f32_e32 v8, v8
	v_rcp_f32_e32 v9, v9
	v_rcp_f32_e32 v10, v10
	v_rcp_f32_e32 v11, v11
	v_rcp_f32_e32 v12, v12
	v_rcp_f32_e32 v13, v13
	v_rcp_f32_e32 v14, v14
	v_rcp_f32_e32 v15, v15
	v_rcp_f32_e32 v18, v18
	v_rcp_f32_e32 v19, v19
	v_rcp_f32_e32 v20, v20
	v_rcp_f32_e32 v21, v21
	v_rcp_f32_e32 v22, v22
	v_rcp_f32_e32 v23, v23
	v_rcp_f32_e32 v24, v24
	v_rcp_f32_e32 v25, v25
	v_rcp_f32_e32 v26, v26
	v_rcp_f32_e32 v27, v27
	v_rcp_f32_e32 v30, v30
	v_rcp_f32_e32 v31, v31
	v_rcp_f32_e32 v36, v36
	v_rcp_f32_e32 v37, v37
	v_rcp_f32_e32 v38, v38
	v_rcp_f32_e32 v39, v39
	v_rcp_f32_e32 v52, v52
	v_rcp_f32_e32 v53, v53
	v_rcp_f32_e32 v54, v54
	v_rcp_f32_e32 v55, v55
	v_pk_mul_f32 v[8:9], v[62:63], v[8:9]
	v_pk_mul_f32 v[10:11], v[56:57], v[10:11]
	v_pk_mul_f32 v[12:13], v[50:51], v[12:13]
	v_pk_mul_f32 v[14:15], v[60:61], v[14:15]
	v_pk_mul_f32 v[18:19], v[58:59], v[18:19]
	v_pk_mul_f32 v[20:21], v[48:49], v[20:21]
	v_pk_mul_f32 v[22:23], v[46:47], v[22:23]
	v_pk_mul_f32 v[24:25], v[42:43], v[24:25]
	v_pk_mul_f32 v[26:27], v[0:1], v[26:27]
	v_pk_mul_f32 v[30:31], v[4:5], v[30:31]
	v_pk_mul_f32 v[36:37], v[6:7], v[36:37]
	v_pk_mul_f32 v[38:39], v[2:3], v[38:39]
	v_pk_mul_f32 v[52:53], v[34:35], v[52:53]
	v_pk_mul_f32 v[54:55], v[28:29], v[54:55]
	s_mov_b64 s[12:13], 0
